# gla_unit<3> first-token f32 score: 128-element dot product fetched by all lanes at once and wave-reduced (was 8 dependent load round trips on the critical workgroups)
# baseline (speedup 1.0000x reference)
.LBB0_46:
	s_nop 7
	v_cndmask_b32_e64 v70, v66, 0, s[22:23]
	v_or_b32_e32 v66, s47, v194
	v_cmp_eq_u32_e32 vcc, 0, v66
	s_and_saveexec_b64 s[0:1], vcc
	s_cbranch_execz .LBB0_50
	s_mov_b64 s[2:3], exec
	s_mov_b64 exec, -1
	v_mbcnt_lo_u32_b32 v132, -1, 0
	v_mbcnt_hi_u32_b32 v132, -1, v132
	v_lshlrev_b32_e32 v132, 3, v132
	global_load_dwordx2 v[134:135], v132, s[60:61]
	global_load_dwordx2 v[136:137], v132, s[60:61] offset:2048
	s_waitcnt vmcnt(0)
	v_mul_f32_e32 v138, v134, v136
	v_fmac_f32_e32 v138, v135, v137
	s_nop 1
	v_add_f32_dpp v138, v138, v138 quad_perm:[1,0,3,2] row_mask:0xf bank_mask:0xf bound_ctrl:1
	s_nop 1
	v_add_f32_dpp v138, v138, v138 quad_perm:[2,3,0,1] row_mask:0xf bank_mask:0xf bound_ctrl:1
	s_nop 1
	v_add_f32_dpp v138, v138, v138 row_half_mirror row_mask:0xf bank_mask:0xf bound_ctrl:1
	s_nop 1
	v_add_f32_dpp v138, v138, v138 row_mirror row_mask:0xf bank_mask:0xf bound_ctrl:1
	s_nop 1
	v_readlane_b32 s64, v138, 0
	v_readlane_b32 s65, v138, 16
	v_readlane_b32 s98, v138, 32
	v_readlane_b32 s99, v138, 48
	s_mov_b64 exec, s[2:3]
	v_mov_b32_e32 v66, s64
	v_add_f32_e32 v66, s65, v66
	v_add_f32_e32 v66, s98, v66
	v_add_f32_e32 v66, s99, v66
	v_mul_f32_e32 v70, 0x3db504f3, v66
